# NSA selected/window loops: fast path and no-rescale route fall-through, slow and rescale blocks out of line (same code motion as MoBA v60)
# baseline (speedup 1.0000x reference)
.LBB0_1020:
	s_nop 4
	v_max3_f32 v216, v64, v65, v66
	v_max3_f32 v217, v67, v68, v69
	v_max3_f32 v216, v216, v70, v71
	v_max3_f32 v217, v217, v72, v73
	v_max3_f32 v216, v216, v74, v75
	v_max3_f32 v217, v217, v76, v77
	v_max3_f32 v216, v216, v78, v79
	v_max3_f32 v217, v217, v48, v49
	v_max3_f32 v216, v216, v50, v51
	v_max3_f32 v217, v217, v52, v53
	v_max3_f32 v216, v216, v54, v55
	v_max3_f32 v217, v217, v56, v57
	v_max3_f32 v216, v216, v58, v59
	v_max3_f32 v217, v217, v60, v61
	v_max3_f32 v216, v216, v62, v63
	v_max_f32_e32 v216, v216, v217
	v_mov_b32_e32 v217, v216
	s_nop 1
	v_permlane32_swap_b32_e32 v217, v216
	v_max_f32_e32 v216, v216, v217
	v_cmp_lt_f32_e32 vcc, s92, v216
	s_cbranch_vccnz .Lse_resc

.LBB0_1026:
	s_add_i32 s4, s2, -2
	v_lshrrev_b32_e32 v48, s4, v128
	v_and_b32_e32 v48, 1, v48
	v_cmp_eq_u32_e64 s[14:15], 1, v48
	v_bfe_u32 v48, v128, s4, 1
	v_cmp_ne_u32_e32 vcc, 0, v48
	s_cbranch_vccz .LBB0_1012
	s_cmp_eq_u32 s12, 2
	s_cbranch_scc1 .Lso_slow
	v_cndmask_b32_e64 v48, v210, 0, s[14:15]
	v_pk_add_f32 v[62:63], v[46:47], v[48:49] op_sel_hi:[1,0]
	v_pk_add_f32 v[60:61], v[44:45], v[48:49] op_sel_hi:[1,0]
	v_pk_add_f32 v[58:59], v[42:43], v[48:49] op_sel_hi:[1,0]
	v_pk_add_f32 v[56:57], v[40:41], v[48:49] op_sel_hi:[1,0]
	v_pk_add_f32 v[54:55], v[38:39], v[48:49] op_sel_hi:[1,0]
	v_pk_add_f32 v[52:53], v[36:37], v[48:49] op_sel_hi:[1,0]
	v_pk_add_f32 v[50:51], v[34:35], v[48:49] op_sel_hi:[1,0]
	v_pk_add_f32 v[48:49], v[32:33], v[48:49] op_sel_hi:[1,0]
	ds_read_b128 v[112:115], v131 offset:9216
	ds_read_b128 v[116:119], v131 offset:9248
	s_waitcnt lgkmcnt(1)
	v_mfma_f32_32x32x16_bf16 v[64:79], v[112:115], v[80:83], v[48:63]
	ds_read_b128 v[112:115], v131 offset:13824
	ds_read_b128 v[120:123], v131 offset:13856
	s_waitcnt lgkmcnt(1)
	v_mfma_f32_32x32x16_bf16 v[48:63], v[112:115], v[80:83], v[48:63]
	v_mfma_f32_32x32x16_bf16 v[64:79], v[116:119], v[84:87], v[64:79]
	ds_read_b128 v[112:115], v131 offset:9280
	ds_read_b128 v[116:119], v131 offset:9312
	s_waitcnt lgkmcnt(2)
	v_mfma_f32_32x32x16_bf16 v[48:63], v[120:123], v[84:87], v[48:63]
	s_waitcnt lgkmcnt(1)
	v_mfma_f32_32x32x16_bf16 v[64:79], v[112:115], v[88:91], v[64:79]
	ds_read_b128 v[112:115], v131 offset:13888
	ds_read_b128 v[218:221], v131 offset:13920
	s_waitcnt lgkmcnt(1)
	v_mfma_f32_32x32x16_bf16 v[48:63], v[112:115], v[88:91], v[48:63]
	v_mfma_f32_32x32x16_bf16 v[64:79], v[116:119], v[92:95], v[64:79]
	ds_read_b64_tr_b16 v[120:121], v160 offset:30720
	ds_read_b64_tr_b16 v[122:123], v160 offset:32256
	ds_read_b64_tr_b16 v[114:115], v160 offset:32320
	ds_read_b64_tr_b16 v[112:113], v160 offset:30784
	ds_read_b64_tr_b16 v[124:125], v160 offset:33792
	ds_read_b64_tr_b16 v[126:127], v160 offset:35328
	ds_read_b64_tr_b16 v[118:119], v160 offset:35392
	ds_read_b64_tr_b16 v[116:117], v160 offset:33856
	s_waitcnt lgkmcnt(8)
	v_mfma_f32_32x32x16_bf16 v[48:63], v[218:221], v[92:95], v[48:63]
.LBB0_1031:
	s_nop 4
	v_max3_f32 v216, v64, v65, v66
	v_max3_f32 v217, v67, v68, v69
	v_max3_f32 v216, v216, v70, v71
	v_max3_f32 v217, v217, v72, v73
	v_max3_f32 v216, v216, v74, v75
	v_max3_f32 v217, v217, v76, v77
	v_max3_f32 v216, v216, v78, v79
	v_max3_f32 v217, v217, v48, v49
	v_max3_f32 v216, v216, v50, v51
	v_max3_f32 v217, v217, v52, v53
	v_max3_f32 v216, v216, v54, v55
	v_max3_f32 v217, v217, v56, v57
	v_max3_f32 v216, v216, v58, v59
	v_max3_f32 v217, v217, v60, v61
	v_max3_f32 v216, v216, v62, v63
	v_max_f32_e32 v216, v216, v217
	v_mov_b32_e32 v217, v216
	s_nop 1
	v_permlane32_swap_b32_e32 v217, v216
	v_max_f32_e32 v216, v216, v217
	v_cmp_lt_f32_e32 vcc, s92, v216
	s_cbranch_vccz .LBB0_1011
	v_max_f32_e32 v32, v216, v216
	v_max_f32_e32 v34, 0, v32
	v_exp_f32_e64 v36, -v34
	v_add_f32_e32 v215, v215, v34
	v_xor_b32_e32 v32, 0x80000000, v215
	v_pk_add_f32 v[64:65], v[64:65], v[34:35] op_sel_hi:[1,0] neg_lo:[0,1] neg_hi:[0,1]
	v_mul_f32_e32 v214, v214, v36
	v_pk_add_f32 v[48:49], v[48:49], v[34:35] op_sel_hi:[1,0] neg_lo:[0,1] neg_hi:[0,1]
	v_pk_add_f32 v[66:67], v[66:67], v[34:35] op_sel_hi:[1,0] neg_lo:[0,1] neg_hi:[0,1]
	v_pk_add_f32 v[50:51], v[50:51], v[34:35] op_sel_hi:[1,0] neg_lo:[0,1] neg_hi:[0,1]
	v_pk_add_f32 v[68:69], v[68:69], v[34:35] op_sel_hi:[1,0] neg_lo:[0,1] neg_hi:[0,1]
	v_pk_add_f32 v[52:53], v[52:53], v[34:35] op_sel_hi:[1,0] neg_lo:[0,1] neg_hi:[0,1]
	v_pk_add_f32 v[70:71], v[70:71], v[34:35] op_sel_hi:[1,0] neg_lo:[0,1] neg_hi:[0,1]
	v_pk_add_f32 v[54:55], v[54:55], v[34:35] op_sel_hi:[1,0] neg_lo:[0,1] neg_hi:[0,1]
	v_pk_add_f32 v[72:73], v[72:73], v[34:35] op_sel_hi:[1,0] neg_lo:[0,1] neg_hi:[0,1]
	v_pk_add_f32 v[56:57], v[56:57], v[34:35] op_sel_hi:[1,0] neg_lo:[0,1] neg_hi:[0,1]
	v_pk_add_f32 v[74:75], v[74:75], v[34:35] op_sel_hi:[1,0] neg_lo:[0,1] neg_hi:[0,1]
	v_pk_add_f32 v[58:59], v[58:59], v[34:35] op_sel_hi:[1,0] neg_lo:[0,1] neg_hi:[0,1]
	v_pk_add_f32 v[76:77], v[76:77], v[34:35] op_sel_hi:[1,0] neg_lo:[0,1] neg_hi:[0,1]
	v_pk_add_f32 v[60:61], v[60:61], v[34:35] op_sel_hi:[1,0] neg_lo:[0,1] neg_hi:[0,1]
	v_pk_add_f32 v[78:79], v[78:79], v[34:35] op_sel_hi:[1,0] neg_lo:[0,1] neg_hi:[0,1]
	v_pk_add_f32 v[62:63], v[62:63], v[34:35] op_sel_hi:[1,0] neg_lo:[0,1] neg_hi:[0,1]
	v_pk_mul_f32 v[30:31], v[30:31], v[36:37] op_sel_hi:[1,0]
	v_pk_mul_f32 v[28:29], v[28:29], v[36:37] op_sel_hi:[1,0]
	v_pk_mul_f32 v[26:27], v[26:27], v[36:37] op_sel_hi:[1,0]
	v_pk_mul_f32 v[24:25], v[24:25], v[36:37] op_sel_hi:[1,0]
	v_pk_mul_f32 v[22:23], v[22:23], v[36:37] op_sel_hi:[1,0]
	v_pk_mul_f32 v[20:21], v[20:21], v[36:37] op_sel_hi:[1,0]
	v_pk_mul_f32 v[18:19], v[18:19], v[36:37] op_sel_hi:[1,0]
	v_pk_mul_f32 v[16:17], v[16:17], v[36:37] op_sel_hi:[1,0]
	v_pk_mul_f32 v[14:15], v[14:15], v[36:37] op_sel_hi:[1,0]
	v_pk_mul_f32 v[12:13], v[12:13], v[36:37] op_sel_hi:[1,0]
	v_pk_mul_f32 v[10:11], v[10:11], v[36:37] op_sel_hi:[1,0]
	v_pk_mul_f32 v[8:9], v[8:9], v[36:37] op_sel_hi:[1,0]
	v_pk_mul_f32 v[6:7], v[6:7], v[36:37] op_sel_hi:[1,0]
	v_pk_mul_f32 v[4:5], v[4:5], v[36:37] op_sel_hi:[1,0]
	v_pk_mul_f32 v[2:3], v[2:3], v[36:37] op_sel_hi:[1,0]
	v_pk_mul_f32 v[0:1], v[0:1], v[36:37] op_sel_hi:[1,0]
	v_mov_b32_e32 v33, v32
	v_mov_b32_e32 v34, v32
	v_mov_b32_e32 v35, v32
	v_mov_b32_e32 v36, v32
	v_mov_b32_e32 v37, v32
	v_mov_b32_e32 v38, v32
	v_mov_b32_e32 v39, v32
	v_mov_b32_e32 v40, v32
	v_mov_b32_e32 v41, v32
	v_mov_b32_e32 v42, v32
	v_mov_b32_e32 v43, v32
	v_mov_b32_e32 v44, v32
	v_mov_b32_e32 v45, v32
	v_mov_b32_e32 v46, v32
	v_mov_b32_e32 v47, v32
	s_branch .LBB0_1011
.Lse_slow:
	s_cmp_eq_u32 s12, 3
	s_cselect_b64 vcc, -1, 0
	v_cndmask_b32_e32 v216, 63, v193, vcc
	v_cmp_eq_u32_e32 vcc, 63, v216
	s_xor_b64 s[4:5], s[14:15], -1
	ds_read_b128 v[112:115], v131
	ds_read_b128 v[116:119], v131 offset:32
	s_or_b64 s[18:19], vcc, s[4:5]
	v_cndmask_b32_e64 v48, 0, 1, s[18:19]
	s_and_b64 s[16:17], vcc, s[14:15]
	v_cmp_ne_u32_e32 vcc, 0, v48
	s_cmp_lg_u64 vcc, exec
	s_cselect_b64 s[18:19], -1, 0
	s_or_b64 s[16:17], s[16:17], s[18:19]
	v_cndmask_b32_e64 v48, v210, 0, s[16:17]
	v_pk_add_f32 v[62:63], v[46:47], v[48:49] op_sel_hi:[1,0]
	v_pk_add_f32 v[60:61], v[44:45], v[48:49] op_sel_hi:[1,0]
	v_pk_add_f32 v[58:59], v[42:43], v[48:49] op_sel_hi:[1,0]
	v_pk_add_f32 v[56:57], v[40:41], v[48:49] op_sel_hi:[1,0]
	v_pk_add_f32 v[54:55], v[38:39], v[48:49] op_sel_hi:[1,0]
	v_pk_add_f32 v[52:53], v[36:37], v[48:49] op_sel_hi:[1,0]
	v_pk_add_f32 v[50:51], v[34:35], v[48:49] op_sel_hi:[1,0]
	v_pk_add_f32 v[48:49], v[32:33], v[48:49] op_sel_hi:[1,0]
	s_cmp_eq_u64 vcc, exec
	s_waitcnt lgkmcnt(1)
	v_mfma_f32_32x32x16_bf16 v[64:79], v[112:115], v[80:83], v[48:63]
	ds_read_b128 v[112:115], v131 offset:4608
	ds_read_b128 v[120:123], v131 offset:4640
	s_waitcnt lgkmcnt(1)
	v_mfma_f32_32x32x16_bf16 v[48:63], v[112:115], v[80:83], v[48:63]
	v_mfma_f32_32x32x16_bf16 v[64:79], v[116:119], v[84:87], v[64:79]
	ds_read_b128 v[112:115], v131 offset:64
	ds_read_b128 v[116:119], v131 offset:96
	s_waitcnt lgkmcnt(2)
	v_mfma_f32_32x32x16_bf16 v[48:63], v[120:123], v[84:87], v[48:63]
	s_waitcnt lgkmcnt(1)
	v_mfma_f32_32x32x16_bf16 v[64:79], v[112:115], v[88:91], v[64:79]
	ds_read_b128 v[112:115], v131 offset:4672
	ds_read_b128 v[218:221], v131 offset:4704
	s_waitcnt lgkmcnt(1)
	v_mfma_f32_32x32x16_bf16 v[48:63], v[112:115], v[88:91], v[48:63]
	v_mfma_f32_32x32x16_bf16 v[64:79], v[116:119], v[92:95], v[64:79]
	ds_read_b64_tr_b16 v[120:121], v160 offset:18432
	ds_read_b64_tr_b16 v[122:123], v160 offset:19968
	ds_read_b64_tr_b16 v[114:115], v160 offset:20032
	ds_read_b64_tr_b16 v[112:113], v160 offset:18496
	ds_read_b64_tr_b16 v[124:125], v160 offset:21504
	ds_read_b64_tr_b16 v[126:127], v160 offset:23040
	ds_read_b64_tr_b16 v[118:119], v160 offset:23104
	ds_read_b64_tr_b16 v[116:117], v160 offset:21568
	s_waitcnt lgkmcnt(8)
	v_mfma_f32_32x32x16_bf16 v[48:63], v[218:221], v[92:95], v[48:63]
	s_cbranch_scc1 .LBB0_1020
	v_cmp_le_u32_e64 s[16:17], v161, v216
	v_cmp_le_u32_e64 s[18:19], v162, v216
	v_cmp_le_u32_e64 s[20:21], v164, v216
	v_cmp_le_u32_e64 s[22:23], v166, v216
	v_cmp_le_u32_e64 s[24:25], v168, v216
	v_cmp_le_u32_e64 s[26:27], v170, v216
	v_cmp_le_u32_e64 s[28:29], v172, v216
	v_cmp_le_u32_e64 s[30:31], v174, v216
	v_cmp_le_u32_e64 s[34:35], v176, v216
	v_cmp_le_u32_e64 s[36:37], v178, v216
	v_cmp_le_u32_e64 s[38:39], v180, v216
	v_cmp_le_u32_e64 s[40:41], v182, v216
	v_cmp_le_u32_e64 s[42:43], v184, v216
	v_cmp_le_u32_e64 s[44:45], v186, v216
	v_cmp_le_u32_e64 s[46:47], v189, v216
	s_and_b64 s[16:17], s[14:15], s[16:17]
	s_and_b64 s[18:19], s[14:15], s[18:19]
	s_and_b64 s[20:21], s[14:15], s[20:21]
	s_and_b64 s[22:23], s[14:15], s[22:23]
	s_and_b64 s[24:25], s[14:15], s[24:25]
	s_and_b64 s[26:27], s[14:15], s[26:27]
	s_and_b64 s[28:29], s[14:15], s[28:29]
	s_and_b64 s[30:31], s[14:15], s[30:31]
	s_and_b64 s[34:35], s[14:15], s[34:35]
	s_and_b64 s[36:37], s[14:15], s[36:37]
	s_and_b64 s[38:39], s[14:15], s[38:39]
	s_and_b64 s[40:41], s[14:15], s[40:41]
	s_and_b64 s[42:43], s[14:15], s[42:43]
	s_and_b64 s[44:45], s[14:15], s[44:45]
	s_and_b64 s[46:47], s[14:15], s[46:47]
	v_cmp_gt_u32_e64 s[48:49], v191, v216
	v_cmp_le_u32_e32 vcc, v138, v216
	v_cndmask_b32_e64 v48, v210, v48, s[16:17]
	v_cmp_lt_u32_e64 s[16:17], v138, v216
	v_cndmask_b32_e64 v49, v210, v49, s[18:19]
	v_cmp_le_u32_e64 s[18:19], v163, v216
	v_cndmask_b32_e64 v50, v210, v50, s[20:21]
	v_cmp_le_u32_e64 s[20:21], v165, v216
	v_cndmask_b32_e64 v51, v210, v51, s[22:23]
	v_cmp_le_u32_e64 s[22:23], v167, v216
	v_cndmask_b32_e64 v52, v210, v52, s[24:25]
	v_cmp_le_u32_e64 s[24:25], v169, v216
	v_cndmask_b32_e64 v53, v210, v53, s[26:27]
	v_cmp_le_u32_e64 s[26:27], v171, v216
	v_cndmask_b32_e64 v54, v210, v54, s[28:29]
	v_cmp_le_u32_e64 s[28:29], v173, v216
	v_cndmask_b32_e64 v55, v210, v55, s[30:31]
	v_cmp_le_u32_e64 s[30:31], v175, v216
	v_cndmask_b32_e64 v56, v210, v56, s[34:35]
	v_cmp_le_u32_e64 s[34:35], v177, v216
	v_cndmask_b32_e64 v57, v210, v57, s[36:37]
	v_cmp_le_u32_e64 s[36:37], v179, v216
	v_cndmask_b32_e64 v58, v210, v58, s[38:39]
	v_cmp_le_u32_e64 s[38:39], v181, v216
	v_cndmask_b32_e64 v59, v210, v59, s[40:41]
	v_cmp_le_u32_e64 s[40:41], v183, v216
	v_cndmask_b32_e64 v60, v210, v60, s[42:43]
	v_cmp_le_u32_e64 s[42:43], v185, v216
	v_cndmask_b32_e64 v61, v210, v61, s[44:45]
	v_cmp_le_u32_e64 s[44:45], v187, v216
	v_cndmask_b32_e64 v62, v210, v62, s[46:47]
	v_cmp_le_u32_e64 s[46:47], v190, v216
	s_or_b64 s[48:49], s[4:5], s[48:49]
	s_and_saveexec_b64 s[4:5], s[48:49]
	v_mov_b32_e32 v63, s33
	s_or_b64 exec, exec, s[4:5]
	s_and_b64 vcc, s[14:15], vcc
	v_cndmask_b32_e32 v64, v210, v64, vcc
	s_and_b64 vcc, s[14:15], s[16:17]
	v_cndmask_b32_e32 v65, v210, v65, vcc
	s_and_b64 vcc, s[14:15], s[18:19]
	v_cndmask_b32_e32 v66, v210, v66, vcc
	s_and_b64 vcc, s[14:15], s[20:21]
	v_cndmask_b32_e32 v67, v210, v67, vcc
	s_and_b64 vcc, s[14:15], s[22:23]
	v_cndmask_b32_e32 v68, v210, v68, vcc
	s_and_b64 vcc, s[14:15], s[24:25]
	v_cndmask_b32_e32 v69, v210, v69, vcc
	s_and_b64 vcc, s[14:15], s[26:27]
	v_cndmask_b32_e32 v70, v210, v70, vcc
	s_and_b64 vcc, s[14:15], s[28:29]
	v_cndmask_b32_e32 v71, v210, v71, vcc
	s_and_b64 vcc, s[14:15], s[30:31]
	v_cndmask_b32_e32 v72, v210, v72, vcc
	s_and_b64 vcc, s[14:15], s[34:35]
	v_cndmask_b32_e32 v73, v210, v73, vcc
	s_and_b64 vcc, s[14:15], s[36:37]
	v_cndmask_b32_e32 v74, v210, v74, vcc
	s_and_b64 vcc, s[14:15], s[38:39]
	v_cndmask_b32_e32 v75, v210, v75, vcc
	s_and_b64 vcc, s[14:15], s[40:41]
	v_cndmask_b32_e32 v76, v210, v76, vcc
	s_and_b64 vcc, s[14:15], s[42:43]
	v_cndmask_b32_e32 v77, v210, v77, vcc
	s_and_b64 vcc, s[14:15], s[44:45]
	v_cndmask_b32_e32 v78, v210, v78, vcc
	s_and_b64 vcc, s[14:15], s[46:47]
	v_cndmask_b32_e32 v79, v210, v79, vcc
	s_branch .LBB0_1020
.Lso_slow:
	s_cmp_eq_u32 s12, 2
	s_cselect_b64 vcc, -1, 0
	v_cndmask_b32_e32 v216, 63, v193, vcc
	v_cmp_eq_u32_e32 vcc, 63, v216
	s_xor_b64 s[4:5], s[14:15], -1
	ds_read_b128 v[112:115], v131 offset:9216
	ds_read_b128 v[116:119], v131 offset:9248
	s_or_b64 s[16:17], vcc, s[4:5]
	v_cndmask_b32_e64 v48, 0, 1, s[16:17]
	s_and_b64 s[12:13], vcc, s[14:15]
	v_cmp_ne_u32_e32 vcc, 0, v48
	s_cmp_lg_u64 vcc, exec
	s_cselect_b64 s[16:17], -1, 0
	s_or_b64 s[12:13], s[12:13], s[16:17]
	v_cndmask_b32_e64 v48, v210, 0, s[12:13]
	v_pk_add_f32 v[62:63], v[46:47], v[48:49] op_sel_hi:[1,0]
	v_pk_add_f32 v[60:61], v[44:45], v[48:49] op_sel_hi:[1,0]
	v_pk_add_f32 v[58:59], v[42:43], v[48:49] op_sel_hi:[1,0]
	v_pk_add_f32 v[56:57], v[40:41], v[48:49] op_sel_hi:[1,0]
	v_pk_add_f32 v[54:55], v[38:39], v[48:49] op_sel_hi:[1,0]
	v_pk_add_f32 v[52:53], v[36:37], v[48:49] op_sel_hi:[1,0]
	v_pk_add_f32 v[50:51], v[34:35], v[48:49] op_sel_hi:[1,0]
	v_pk_add_f32 v[48:49], v[32:33], v[48:49] op_sel_hi:[1,0]
	s_cmp_eq_u64 vcc, exec
	s_waitcnt lgkmcnt(1)
	v_mfma_f32_32x32x16_bf16 v[64:79], v[112:115], v[80:83], v[48:63]
	ds_read_b128 v[112:115], v131 offset:13824
	ds_read_b128 v[120:123], v131 offset:13856
	s_waitcnt lgkmcnt(1)
	v_mfma_f32_32x32x16_bf16 v[48:63], v[112:115], v[80:83], v[48:63]
	v_mfma_f32_32x32x16_bf16 v[64:79], v[116:119], v[84:87], v[64:79]
	ds_read_b128 v[112:115], v131 offset:9280
	ds_read_b128 v[116:119], v131 offset:9312
	s_waitcnt lgkmcnt(2)
	v_mfma_f32_32x32x16_bf16 v[48:63], v[120:123], v[84:87], v[48:63]
	s_waitcnt lgkmcnt(1)
	v_mfma_f32_32x32x16_bf16 v[64:79], v[112:115], v[88:91], v[64:79]
	ds_read_b128 v[112:115], v131 offset:13888
	ds_read_b128 v[218:221], v131 offset:13920
	s_waitcnt lgkmcnt(1)
	v_mfma_f32_32x32x16_bf16 v[48:63], v[112:115], v[88:91], v[48:63]
	v_mfma_f32_32x32x16_bf16 v[64:79], v[116:119], v[92:95], v[64:79]
	ds_read_b64_tr_b16 v[120:121], v160 offset:30720
	ds_read_b64_tr_b16 v[122:123], v160 offset:32256
	ds_read_b64_tr_b16 v[114:115], v160 offset:32320
	ds_read_b64_tr_b16 v[112:113], v160 offset:30784
	ds_read_b64_tr_b16 v[124:125], v160 offset:33792
	ds_read_b64_tr_b16 v[126:127], v160 offset:35328
	ds_read_b64_tr_b16 v[118:119], v160 offset:35392
	ds_read_b64_tr_b16 v[116:117], v160 offset:33856
	s_waitcnt lgkmcnt(8)
	v_mfma_f32_32x32x16_bf16 v[48:63], v[218:221], v[92:95], v[48:63]
	s_cbranch_scc1 .LBB0_1031
	v_cmp_le_u32_e64 s[16:17], v161, v216
	v_cmp_le_u32_e64 s[18:19], v162, v216
	v_cmp_le_u32_e64 s[20:21], v164, v216
	v_cmp_le_u32_e64 s[22:23], v166, v216
	v_cmp_le_u32_e64 s[24:25], v168, v216
	v_cmp_le_u32_e64 s[26:27], v170, v216
	v_cmp_le_u32_e64 s[28:29], v172, v216
	v_cmp_le_u32_e64 s[30:31], v174, v216
	v_cmp_le_u32_e64 s[34:35], v176, v216
	v_cmp_le_u32_e64 s[36:37], v178, v216
	v_cmp_le_u32_e64 s[38:39], v180, v216
	v_cmp_le_u32_e64 s[40:41], v182, v216
	v_cmp_le_u32_e64 s[42:43], v184, v216
	v_cmp_le_u32_e64 s[44:45], v186, v216
	v_cmp_le_u32_e64 s[46:47], v189, v216
	s_and_b64 s[16:17], s[14:15], s[16:17]
	s_and_b64 s[18:19], s[14:15], s[18:19]
	s_and_b64 s[20:21], s[14:15], s[20:21]
	s_and_b64 s[22:23], s[14:15], s[22:23]
	s_and_b64 s[24:25], s[14:15], s[24:25]
	s_and_b64 s[26:27], s[14:15], s[26:27]
	s_and_b64 s[28:29], s[14:15], s[28:29]
	s_and_b64 s[30:31], s[14:15], s[30:31]
	s_and_b64 s[34:35], s[14:15], s[34:35]
	s_and_b64 s[36:37], s[14:15], s[36:37]
	s_and_b64 s[38:39], s[14:15], s[38:39]
	s_and_b64 s[40:41], s[14:15], s[40:41]
	s_and_b64 s[42:43], s[14:15], s[42:43]
	s_and_b64 s[44:45], s[14:15], s[44:45]
	s_and_b64 s[46:47], s[14:15], s[46:47]
	v_cmp_gt_u32_e64 s[48:49], v191, v216
	v_cmp_le_u32_e32 vcc, v138, v216
	v_cndmask_b32_e64 v48, v210, v48, s[16:17]
	v_cmp_lt_u32_e64 s[16:17], v138, v216
	v_cndmask_b32_e64 v49, v210, v49, s[18:19]
	v_cmp_le_u32_e64 s[18:19], v163, v216
	v_cndmask_b32_e64 v50, v210, v50, s[20:21]
	v_cmp_le_u32_e64 s[20:21], v165, v216
	v_cndmask_b32_e64 v51, v210, v51, s[22:23]
	v_cmp_le_u32_e64 s[22:23], v167, v216
	v_cndmask_b32_e64 v52, v210, v52, s[24:25]
	v_cmp_le_u32_e64 s[24:25], v169, v216
	v_cndmask_b32_e64 v53, v210, v53, s[26:27]
	v_cmp_le_u32_e64 s[26:27], v171, v216
	v_cndmask_b32_e64 v54, v210, v54, s[28:29]
	v_cmp_le_u32_e64 s[28:29], v173, v216
	v_cndmask_b32_e64 v55, v210, v55, s[30:31]
	v_cmp_le_u32_e64 s[30:31], v175, v216
	v_cndmask_b32_e64 v56, v210, v56, s[34:35]
	v_cmp_le_u32_e64 s[34:35], v177, v216
	v_cndmask_b32_e64 v57, v210, v57, s[36:37]
	v_cmp_le_u32_e64 s[36:37], v179, v216
	v_cndmask_b32_e64 v58, v210, v58, s[38:39]
	v_cmp_le_u32_e64 s[38:39], v181, v216
	v_cndmask_b32_e64 v59, v210, v59, s[40:41]
	v_cmp_le_u32_e64 s[40:41], v183, v216
	v_cndmask_b32_e64 v60, v210, v60, s[42:43]
	v_cmp_le_u32_e64 s[42:43], v185, v216
	v_cndmask_b32_e64 v61, v210, v61, s[44:45]
	v_cmp_le_u32_e64 s[44:45], v187, v216
	v_cndmask_b32_e64 v62, v210, v62, s[46:47]
	v_cmp_le_u32_e64 s[46:47], v190, v216
	s_or_b64 s[12:13], s[4:5], s[48:49]
	s_and_saveexec_b64 s[4:5], s[12:13]
	v_mov_b32_e32 v63, s33
	s_or_b64 exec, exec, s[4:5]
	s_and_b64 vcc, s[14:15], vcc
	v_cndmask_b32_e32 v64, v210, v64, vcc
	s_and_b64 vcc, s[14:15], s[16:17]
	v_cndmask_b32_e32 v65, v210, v65, vcc
	s_and_b64 vcc, s[14:15], s[18:19]
	v_cndmask_b32_e32 v66, v210, v66, vcc
	s_and_b64 vcc, s[14:15], s[20:21]
	v_cndmask_b32_e32 v67, v210, v67, vcc
	s_and_b64 vcc, s[14:15], s[22:23]
	v_cndmask_b32_e32 v68, v210, v68, vcc
	s_and_b64 vcc, s[14:15], s[24:25]
	v_cndmask_b32_e32 v69, v210, v69, vcc
	s_and_b64 vcc, s[14:15], s[26:27]
	v_cndmask_b32_e32 v70, v210, v70, vcc
	s_and_b64 vcc, s[14:15], s[28:29]
	v_cndmask_b32_e32 v71, v210, v71, vcc
	s_and_b64 vcc, s[14:15], s[30:31]
	v_cndmask_b32_e32 v72, v210, v72, vcc
	s_and_b64 vcc, s[14:15], s[34:35]
	v_cndmask_b32_e32 v73, v210, v73, vcc
	s_and_b64 vcc, s[14:15], s[36:37]
	v_cndmask_b32_e32 v74, v210, v74, vcc
	s_and_b64 vcc, s[14:15], s[38:39]
	v_cndmask_b32_e32 v75, v210, v75, vcc
	s_and_b64 vcc, s[14:15], s[40:41]
	v_cndmask_b32_e32 v76, v210, v76, vcc
	s_and_b64 vcc, s[14:15], s[42:43]
	v_cndmask_b32_e32 v77, v210, v77, vcc
	s_and_b64 vcc, s[14:15], s[44:45]
	v_cndmask_b32_e32 v78, v210, v78, vcc
	s_and_b64 vcc, s[14:15], s[46:47]
	v_cndmask_b32_e32 v79, v210, v79, vcc
	s_branch .LBB0_1031
.Lse_resc:
	v_max_f32_e32 v32, v216, v216
	v_max_f32_e32 v34, 0, v32
	v_exp_f32_e64 v36, -v34
	v_add_f32_e32 v215, v215, v34
	v_xor_b32_e32 v32, 0x80000000, v215
	v_pk_add_f32 v[64:65], v[64:65], v[34:35] op_sel_hi:[1,0] neg_lo:[0,1] neg_hi:[0,1]
	v_mul_f32_e32 v214, v214, v36
	v_pk_add_f32 v[48:49], v[48:49], v[34:35] op_sel_hi:[1,0] neg_lo:[0,1] neg_hi:[0,1]
	v_pk_add_f32 v[66:67], v[66:67], v[34:35] op_sel_hi:[1,0] neg_lo:[0,1] neg_hi:[0,1]
	v_pk_add_f32 v[50:51], v[50:51], v[34:35] op_sel_hi:[1,0] neg_lo:[0,1] neg_hi:[0,1]
	v_pk_add_f32 v[68:69], v[68:69], v[34:35] op_sel_hi:[1,0] neg_lo:[0,1] neg_hi:[0,1]
	v_pk_add_f32 v[52:53], v[52:53], v[34:35] op_sel_hi:[1,0] neg_lo:[0,1] neg_hi:[0,1]
	v_pk_add_f32 v[70:71], v[70:71], v[34:35] op_sel_hi:[1,0] neg_lo:[0,1] neg_hi:[0,1]
	v_pk_add_f32 v[54:55], v[54:55], v[34:35] op_sel_hi:[1,0] neg_lo:[0,1] neg_hi:[0,1]
	v_pk_add_f32 v[72:73], v[72:73], v[34:35] op_sel_hi:[1,0] neg_lo:[0,1] neg_hi:[0,1]
	v_pk_add_f32 v[56:57], v[56:57], v[34:35] op_sel_hi:[1,0] neg_lo:[0,1] neg_hi:[0,1]
	v_pk_add_f32 v[74:75], v[74:75], v[34:35] op_sel_hi:[1,0] neg_lo:[0,1] neg_hi:[0,1]
	v_pk_add_f32 v[58:59], v[58:59], v[34:35] op_sel_hi:[1,0] neg_lo:[0,1] neg_hi:[0,1]
	v_pk_add_f32 v[76:77], v[76:77], v[34:35] op_sel_hi:[1,0] neg_lo:[0,1] neg_hi:[0,1]
	v_pk_add_f32 v[60:61], v[60:61], v[34:35] op_sel_hi:[1,0] neg_lo:[0,1] neg_hi:[0,1]
	v_pk_add_f32 v[78:79], v[78:79], v[34:35] op_sel_hi:[1,0] neg_lo:[0,1] neg_hi:[0,1]
	v_pk_add_f32 v[62:63], v[62:63], v[34:35] op_sel_hi:[1,0] neg_lo:[0,1] neg_hi:[0,1]
	v_pk_mul_f32 v[30:31], v[30:31], v[36:37] op_sel_hi:[1,0]
	v_pk_mul_f32 v[28:29], v[28:29], v[36:37] op_sel_hi:[1,0]
	v_pk_mul_f32 v[26:27], v[26:27], v[36:37] op_sel_hi:[1,0]
	v_pk_mul_f32 v[24:25], v[24:25], v[36:37] op_sel_hi:[1,0]
	v_pk_mul_f32 v[22:23], v[22:23], v[36:37] op_sel_hi:[1,0]
	v_pk_mul_f32 v[20:21], v[20:21], v[36:37] op_sel_hi:[1,0]
	v_pk_mul_f32 v[18:19], v[18:19], v[36:37] op_sel_hi:[1,0]
	v_pk_mul_f32 v[16:17], v[16:17], v[36:37] op_sel_hi:[1,0]
	v_pk_mul_f32 v[14:15], v[14:15], v[36:37] op_sel_hi:[1,0]
	v_pk_mul_f32 v[12:13], v[12:13], v[36:37] op_sel_hi:[1,0]
	v_pk_mul_f32 v[10:11], v[10:11], v[36:37] op_sel_hi:[1,0]
	v_pk_mul_f32 v[8:9], v[8:9], v[36:37] op_sel_hi:[1,0]
	v_pk_mul_f32 v[6:7], v[6:7], v[36:37] op_sel_hi:[1,0]
	v_pk_mul_f32 v[4:5], v[4:5], v[36:37] op_sel_hi:[1,0]
	v_pk_mul_f32 v[2:3], v[2:3], v[36:37] op_sel_hi:[1,0]
	v_pk_mul_f32 v[0:1], v[0:1], v[36:37] op_sel_hi:[1,0]
	v_mov_b32_e32 v33, v32
	v_mov_b32_e32 v34, v32
	v_mov_b32_e32 v35, v32
	v_mov_b32_e32 v36, v32
	v_mov_b32_e32 v37, v32
	v_mov_b32_e32 v38, v32
	v_mov_b32_e32 v39, v32
	v_mov_b32_e32 v40, v32
	v_mov_b32_e32 v41, v32
	v_mov_b32_e32 v42, v32
	v_mov_b32_e32 v43, v32
	v_mov_b32_e32 v44, v32
	v_mov_b32_e32 v45, v32
	v_mov_b32_e32 v46, v32
	v_mov_b32_e32 v47, v32
	s_branch .LBB0_1022

.LBB0_1182:
	s_andn2_b64 vcc, exec, s[94:95]
	s_cbranch_vccz .LBB0_1184
	s_mov_b32 s13, s12
	s_branch .LBB0_1037
.Lwe_slow:
	s_cmp_lg_u32 s3, s13
	s_cselect_b64 s[4:5], -1, 0
	s_cmp_eq_u32 s1, s13
	s_cselect_b64 vcc, -1, 0
	v_cndmask_b32_e64 v216, v205, 0, s[4:5]
	v_cndmask_b32_e32 v217, 63, v193, vcc
	v_cmp_le_u32_e32 vcc, v216, v217
	v_cmp_gt_u32_e64 s[14:15], 64, v216
	s_and_b64 vcc, s[14:15], vcc
	s_cbranch_vccz .LBB0_1109
	v_cmp_eq_u32_e64 s[14:15], 63, v217
	s_and_b64 s[16:17], s[4:5], s[14:15]
	s_xor_b64 s[4:5], vcc, -1
	ds_read_b128 v[112:115], v131
	ds_read_b128 v[116:119], v131 offset:32
	s_or_b64 s[14:15], s[16:17], s[4:5]
	v_cndmask_b32_e64 v48, 0, 1, s[14:15]
	v_cmp_ne_u32_e64 s[14:15], 0, v48
	s_cmp_lg_u64 s[14:15], exec
	s_cselect_b64 s[18:19], -1, 0
	s_or_b64 s[16:17], s[16:17], s[18:19]
	v_cndmask_b32_e64 v48, v210, 0, s[16:17]
	v_pk_add_f32 v[62:63], v[46:47], v[48:49] op_sel_hi:[1,0]
	v_pk_add_f32 v[60:61], v[44:45], v[48:49] op_sel_hi:[1,0]
	v_pk_add_f32 v[58:59], v[42:43], v[48:49] op_sel_hi:[1,0]
	v_pk_add_f32 v[56:57], v[40:41], v[48:49] op_sel_hi:[1,0]
	v_pk_add_f32 v[54:55], v[38:39], v[48:49] op_sel_hi:[1,0]
	v_pk_add_f32 v[52:53], v[36:37], v[48:49] op_sel_hi:[1,0]
	v_pk_add_f32 v[50:51], v[34:35], v[48:49] op_sel_hi:[1,0]
	v_pk_add_f32 v[48:49], v[32:33], v[48:49] op_sel_hi:[1,0]
	s_cmp_eq_u64 s[14:15], exec
	s_waitcnt lgkmcnt(1)
	v_mfma_f32_32x32x16_bf16 v[64:79], v[112:115], v[80:83], v[48:63]
	ds_read_b128 v[112:115], v131 offset:4608
	ds_read_b128 v[120:123], v131 offset:4640
	s_waitcnt lgkmcnt(1)
	v_mfma_f32_32x32x16_bf16 v[48:63], v[112:115], v[80:83], v[48:63]
	v_mfma_f32_32x32x16_bf16 v[64:79], v[116:119], v[84:87], v[64:79]
	ds_read_b128 v[112:115], v131 offset:64
	ds_read_b128 v[116:119], v131 offset:96
	s_waitcnt lgkmcnt(2)
	v_mfma_f32_32x32x16_bf16 v[48:63], v[120:123], v[84:87], v[48:63]
	s_waitcnt lgkmcnt(1)
	v_mfma_f32_32x32x16_bf16 v[64:79], v[112:115], v[88:91], v[64:79]
	ds_read_b128 v[112:115], v131 offset:4672
	ds_read_b128 v[218:221], v131 offset:4704
	s_waitcnt lgkmcnt(1)
	v_mfma_f32_32x32x16_bf16 v[48:63], v[112:115], v[88:91], v[48:63]
	v_mfma_f32_32x32x16_bf16 v[64:79], v[116:119], v[92:95], v[64:79]
	ds_read_b64_tr_b16 v[120:121], v160 offset:18432
	ds_read_b64_tr_b16 v[122:123], v160 offset:19968
	ds_read_b64_tr_b16 v[114:115], v160 offset:20032
	ds_read_b64_tr_b16 v[112:113], v160 offset:18496
	ds_read_b64_tr_b16 v[124:125], v160 offset:21504
	ds_read_b64_tr_b16 v[126:127], v160 offset:23040
	ds_read_b64_tr_b16 v[118:119], v160 offset:23104
	ds_read_b64_tr_b16 v[116:117], v160 offset:21568
	s_waitcnt lgkmcnt(8)
	v_mfma_f32_32x32x16_bf16 v[48:63], v[218:221], v[92:95], v[48:63]
	s_cbranch_scc1 .LBB0_1106
	s_mov_b64 s[14:15], s[4:5]
	s_and_saveexec_b64 s[18:19], vcc
	s_cbranch_execz .LBB0_1071
	v_cmp_lt_u32_e64 s[14:15], v161, v216
	v_cmp_gt_u32_e64 s[16:17], v161, v217
	s_or_b64 s[14:15], s[14:15], s[16:17]
	s_andn2_b64 s[16:17], s[4:5], exec
	s_and_b64 s[14:15], s[14:15], exec
	s_or_b64 s[14:15], s[16:17], s[14:15]
	s_or_b64 exec, exec, s[18:19]
	s_and_saveexec_b64 s[16:17], s[14:15]
	s_cbranch_execnz .LBB0_1072

.LBB0_1103:
	s_or_b64 exec, exec, s[88:89]
	s_and_saveexec_b64 s[80:81], s[4:5]
	v_mov_b32_e32 v63, s33
	s_or_b64 exec, exec, s[80:81]
	s_and_b64 s[4:5], s[74:75], s[78:79]
	s_and_b64 s[74:75], vcc, s[4:5]
	s_and_b64 s[4:5], s[70:71], s[76:77]
	s_and_b64 s[70:71], vcc, s[4:5]
	s_and_b64 s[4:5], s[66:67], s[72:73]
	s_and_b64 s[66:67], vcc, s[4:5]
	s_and_b64 s[4:5], s[62:63], s[68:69]
	s_and_b64 s[62:63], vcc, s[4:5]
	s_and_b64 s[4:5], s[58:59], s[64:65]
	s_and_b64 s[58:59], vcc, s[4:5]
	s_and_b64 s[4:5], s[54:55], s[60:61]
	s_and_b64 s[54:55], vcc, s[4:5]
	s_and_b64 s[4:5], s[50:51], s[56:57]
	s_and_b64 s[50:51], vcc, s[4:5]
	s_and_b64 s[4:5], s[46:47], s[52:53]
	s_and_b64 s[46:47], vcc, s[4:5]
	s_and_b64 s[4:5], s[42:43], s[48:49]
	s_and_b64 s[42:43], vcc, s[4:5]
	s_and_b64 s[4:5], s[38:39], s[44:45]
	s_and_b64 s[38:39], vcc, s[4:5]
	s_and_b64 s[4:5], s[34:35], s[40:41]
	s_and_b64 s[34:35], vcc, s[4:5]
	s_and_b64 s[4:5], s[28:29], s[36:37]
	s_and_b64 s[28:29], vcc, s[4:5]
	s_and_b64 s[4:5], s[24:25], s[30:31]
	s_and_b64 s[24:25], vcc, s[4:5]
	s_and_b64 s[4:5], s[20:21], s[26:27]
	s_and_b64 s[20:21], vcc, s[4:5]
	s_and_b64 s[4:5], s[16:17], s[22:23]
	s_and_b64 s[16:17], vcc, s[4:5]
	s_and_b64 s[4:5], s[14:15], s[18:19]
	s_and_b64 vcc, vcc, s[4:5]
	v_cndmask_b32_e64 v64, v210, v64, s[74:75]
	v_cndmask_b32_e64 v65, v210, v65, s[70:71]
	v_cndmask_b32_e64 v66, v210, v66, s[66:67]
	v_cndmask_b32_e64 v67, v210, v67, s[62:63]
	v_cndmask_b32_e64 v68, v210, v68, s[58:59]
	v_cndmask_b32_e64 v69, v210, v69, s[54:55]
	v_cndmask_b32_e64 v70, v210, v70, s[50:51]
	v_cndmask_b32_e64 v71, v210, v71, s[46:47]
	v_cndmask_b32_e64 v72, v210, v72, s[42:43]
	v_cndmask_b32_e64 v73, v210, v73, s[38:39]
	v_cndmask_b32_e64 v74, v210, v74, s[34:35]
	v_cndmask_b32_e64 v75, v210, v75, s[28:29]
	v_cndmask_b32_e64 v76, v210, v76, s[24:25]
	v_cndmask_b32_e64 v77, v210, v77, s[20:21]
	v_cndmask_b32_e64 v78, v210, v78, s[16:17]
	v_cndmask_b32_e32 v79, v210, v79, vcc
	s_branch .LBB0_1106
